# v55 + the grid sync between latent residual tiles and the [context tiles || pre-norm] phase is an XCD-local barrier (ops 10, 13 and odd-layer op 2); workgroups 0-63 only arrive
# speedup vs baseline: 1.0094x; 1.0094x over previous
; #define GLOBAL_PTR(T, p) ((T*)(__attribute__((address_space(1))) T*)(launder_u64((unsigned long long)(p))))
; DI const float* in_ptr(const Args& AR, int i) { asm volatile("" : "+s"(i)); return GLOBAL_PTR(const float, AR.in[i]); }
; #define GRID_SYNC() do { nbar += (unsigned)gridDim.x; grid_barrier(barw, nbar); } while (0)
; __global__ void __launch_bounds__(512, 2) fwd_megakernel(Args args) {
;     ...
;     unsigned* barw = GLOBAL_PTR(unsigned, args.ws); unsigned nbar = 0u;
;     grid.sync();
;     if (PM & 1) prologue_a(F, AR, 5, 6);
;     GRID_SYNC();
;     if (PM & 2) prologue_b(F, AR);
;     GRID_SYNC();
; #pragma unroll 1
;     for (int k_ = 0; k_ < 2; ++k_) {
;         if ((k_ == 0) == ((blockIdx.x & 1) != 0)) norm_phase(F, in_ptr(AR, 0), in_ptr(AR, 2), in_ptr(AR, 4), WSP(float, WS_MOD), 0);
;         else prologue_a(F, AR, 0, 5);
;     }
;     GRID_SYNC();
;     enum { T_NOP = 0, T_NORM, T_SWI, T_RES, T_STORE, T_FT, T_POST, T_SGU, T_ATTE, T_ATTO };
; #pragma unroll 1
;     for (int l = 0; l < 4; ++l) {
;         const bool even = (l & 1) == 0; const int li = l >> 1;
; #pragma unroll 1
;         for (int op = 0; op < 14; ++op) {
.LBB0_183:
	s_or_b64 exec, exec, s[4:5]
	s_add_i32 s2, 0, 0x12000
	v_writelane_b32 v255, s2, 29
	s_add_i32 s2, 0, 0x18810
	s_mov_b64 s[36:37], 0
	s_mov_b32 s21, 0
	s_mov_b32 s96, 0x3e38aa3b
	v_mov_b32_e32 v1, 0
	v_mov_b32_e32 v162, 0x358637bd
	s_mov_b32 s27, 0x800000
	s_mov_b32 s48, 0xf800000
	v_mov_b32_e32 v187, 0x260
	s_mov_b64 s[24:25], 0x80
	v_writelane_b32 v255, s2, 30
	s_movk_i32 s38, 0x1600
	v_mov_b32_e32 v193, 1
	s_barrier
	s_mov_b32 s98, 0
	s_mov_b32 s100, 0
	s_mov_b32 s99, 0
	s_nop 0
	v_writelane_b32 v255, s99, 60
	s_mov_b32 s101, 0x880f
	s_branch .LBB0_185

; #define GRID_SYNC() do { nbar += (unsigned)gridDim.x; grid_barrier(barw, nbar); } while (0)
; DI void grid_barrier(unsigned* cnt, unsigned target) {
;     asm volatile("s_waitcnt vmcnt(0) lgkmcnt(0)" ::: "memory");
;     __syncthreads();
;     if (threadIdx.x == 0) {
;         __builtin_amdgcn_fence(__ATOMIC_RELEASE, "agent");
;         asm volatile("s_waitcnt vmcnt(0)" ::: "memory");
;         __hip_atomic_fetch_add(cnt, 1u, __ATOMIC_RELAXED, __HIP_MEMORY_SCOPE_AGENT);
;         while (__hip_atomic_load(cnt, __ATOMIC_RELAXED, __HIP_MEMORY_SCOPE_AGENT) < target) __builtin_amdgcn_s_sleep(2);
;         __builtin_amdgcn_fence(__ATOMIC_ACQUIRE, "agent");
;         asm volatile("s_waitcnt vmcnt(0)" ::: "memory");
;     }
;     __syncthreads();
; }
; __global__ void __launch_bounds__(512, 2) fwd_megakernel(Args args) {
;     ...
;             if (!(op == 4 || op == 6 || op == 7 || skip0)) GRID_SYNC();
.Lcs_b_normal:
	s_waitcnt lgkmcnt(0)
	s_cmp_eq_u32 s13, 0x100
	s_cbranch_scc0 .Lxl_no
	s_cmp_eq_u32 s44, 2
	s_cbranch_scc0 .Lxl_not2
	s_bitcmp1_b32 s36, 0
	s_cbranch_scc1 .Lxl_yes
	s_branch .Lxl_no
.Lxl_not2:
	s_cmp_eq_u32 s36, 3
	s_cbranch_scc1 .Lxl_no
	s_cmp_eq_u32 s44, 10
	s_cbranch_scc1 .Lxl_yes
	s_cmp_eq_u32 s44, 13
	s_cbranch_scc0 .Lxl_no
.Lxl_yes:
	s_waitcnt vmcnt(0) lgkmcnt(0)
	s_barrier
	v_readlane_b32 s10, v255, 60
	s_add_u32 s10, s10, 1
	s_nop 0
	v_writelane_b32 v255, s10, 60
	s_lshl_b32 s10, s10, 5
	v_readlane_b32 s2, v255, 0
	s_mov_b64 s[4:5], exec
	v_readlane_b32 s6, v255, 3
	v_readlane_b32 s7, v255, 4
	s_and_b64 s[6:7], s[4:5], s[6:7]
	s_mov_b64 exec, s[6:7]
	s_cbranch_execz .Lxl_done
	s_and_b32 s3, s2, 7
	s_lshl_b32 s3, s3, 2
	s_add_u32 s8, s14, s3
	s_addc_u32 s9, s15, 0
	v_mov_b32_e32 v0, 1
	global_atomic_add v1, v0, s[8:9] offset:128
	s_cmp_lt_u32 s2, 64
	s_cbranch_scc1 .Lxl_done
.Lxl_poll:
	global_load_dword v0, v1, s[8:9] offset:128 sc1
	s_waitcnt vmcnt(0)
	v_cmp_gt_u32_e32 vcc, s10, v0
	s_cbranch_vccz .Lxl_done
	s_sleep 1
	s_branch .Lxl_poll
.Lxl_done:
	s_mov_b64 exec, s[4:5]
	s_barrier
	s_mov_b32 s98, 1
	s_mov_b32 s48, 0xf800000
	s_branch .LBB0_188
